# bh2 variant: role alternation groups interleaved (every 4th workgroup keeps the original section order)
# baseline (speedup 1.0000x reference)
; #define SUB(k, bit) (!(kargs()->li == 1 && (k) == lo) || ((kargs()->submask >> (bit)) & 1u))
; __global__ void __launch_bounds__(NWAVES * 64, 2) fwd(Args args_unused) {
;     ...
;         if (IN(pb + 3)) {
;             PH_PTRS PH_LAYER
;             if (SUB(pb + 3, 0)) {
;                 const int nitems = (M / 16) * 5;
.LBB0_1364:
	v_readlane_b32 s99, v254, 3
	s_nop 3
	s_lshr_b32 s99, s99, 0
	s_and_b32 s99, s99, 3
	s_mov_b32 s98, 2
	s_cmp_eq_u32 s99, 1
	s_cselect_b32 s98, 0, s98
	s_cmp_eq_u32 s99, 2
	s_cselect_b32 s98, 0, s98
	s_cmp_eq_u32 s99, 3
	s_cselect_b32 s98, 0, s98
